# RG-LRU tile-B flush fast path: 8 masked stores with per-row compare/saveexec/branch/address rebuild -> one address + 8 plain stores (consecutive rows, +2048 B) when the whole tile is in range
# speedup vs baseline: 1.0020x; 1.0020x over previous
; __device__ __forceinline__ bf16_t f2bf(float f) { return (bf16_t)(cvt_pk_bf16(f, 0.f) & 0xffffu); }
; __device__ __forceinline__ float siluf_(float x) { return x * __builtin_amdgcn_rcpf(1.f + __expf(-x)); }
; __device__ __forceinline__ void rglru_unit(const Params& p, const WS& ws, int j, int u, bool dry = false) {
;     ...
;   auto flush_y = [&]() {
;     if (ypend_t0 >= 0) {
; #pragma unroll
;       for (int i = 0; i < 8; ++i) {
;         const int t = ypend_t0 + 8 * ssg + i;
;         if (t < T_ && !dry) ws.GA[(size_t)(b * T_ + t) * 1024 + 128 * g + 32 * jq + sc] = ypend[i];
;       }
;     }
;   };
;     ...
;     float hin = CARRY[sc];
; #pragma unroll
;     for (int s2 = 0; s2 < 7; ++s2)
;       if (s2 < ssg) hin = SEGA[s2 * 32 + sc] * hin + SEGH[s2 * 32 + sc];
;     __syncthreads();
;     {
;       float h = hin;
; #pragma unroll
;       for (int i = 0; i < 8; ++i) {
;         const float a = AUa[(8 * ssg + i) * 33 + sc], uu = AUu[(8 * ssg + i) * 33 + sc];
;         h = a * h + uu;
;         const int t = t0 + 8 * ssg + i;
;         ypend[i] = f2bf(h * siluf_(gcur[i]));
;       }
;       if (ssg == 7) CARRY[sc] = h;
;       ypend_t0 = t0;
.LBB0_1460:
	s_or_b64 exec, exec, s[4:5]
	s_waitcnt lgkmcnt(0)
	s_barrier
	ds_read2_b32 v[14:15], v137 offset1:33
	ds_read2_b32 v[56:57], v138 offset0:64 offset1:97
	s_waitcnt lgkmcnt(0)
	v_fma_f32 v56, v13, v14, v56
	v_fmac_f32_e32 v57, v56, v15
	ds_read2_b32 v[14:15], v137 offset0:66 offset1:99
	ds_read2_b32 v[54:55], v138 offset0:130 offset1:163
	s_waitcnt lgkmcnt(0)
	v_fma_f32 v54, v57, v14, v54
	v_fmac_f32_e32 v55, v54, v15
	ds_read2_b32 v[14:15], v137 offset0:132 offset1:165
	ds_read2_b32 v[52:53], v138 offset0:196 offset1:229
	s_waitcnt lgkmcnt(0)
	v_fma_f32 v52, v55, v14, v52
	v_fmac_f32_e32 v53, v52, v15
	ds_read2_b32 v[58:59], v137 offset0:198 offset1:231
	ds_read2_b32 v[14:15], v140 offset0:6 offset1:39
	s_waitcnt lgkmcnt(0)
	v_fma_f32 v13, v53, v58, v14
	v_fmac_f32_e32 v15, v13, v59
	s_and_saveexec_b64 s[4:5], s[50:51]
	ds_write_b32 v115, v15 offset:53760
	s_or_b64 exec, exec, s[4:5]
	v_lshlrev_b32_e32 v14, 16, v120
	v_mul_f32_e32 v58, 0xbfb8aa3b, v14
	v_exp_f32_e32 v58, v58
	v_lshlrev_b32_e32 v59, 16, v119
	v_lshlrev_b32_e32 v60, 16, v122
	v_lshlrev_b32_e32 v61, 16, v121
	v_add_f32_e32 v58, 1.0, v58
	v_rcp_f32_e32 v58, v58
	v_lshlrev_b32_e32 v62, 16, v124
	v_lshlrev_b32_e32 v63, 16, v123
	v_lshlrev_b32_e32 v64, 16, v128
	v_mul_f32_e32 v14, v58, v14
	v_mul_f32_e32 v14, v14, v56
	v_cvt_pk_bf16_f32 v58, v14, s0
	v_mul_f32_e32 v14, 0xbfb8aa3b, v59
	v_exp_f32_e32 v14, v14
	v_lshlrev_b32_e32 v65, 16, v127
	s_cmp_gt_u32 s7, 32
	v_add_f32_e32 v14, 1.0, v14
	v_rcp_f32_e32 v14, v14
	s_nop 0
	v_mul_f32_e32 v14, v14, v59
	v_mul_f32_e32 v14, v14, v57
	v_cvt_pk_bf16_f32 v59, v14, s0
	v_mul_f32_e32 v14, 0xbfb8aa3b, v60
	v_exp_f32_e32 v14, v14
	s_nop 0
	v_add_f32_e32 v14, 1.0, v14
	v_rcp_f32_e32 v14, v14
	s_nop 0
	v_mul_f32_e32 v14, v14, v60
	v_mul_f32_e32 v14, v14, v54
	v_cvt_pk_bf16_f32 v56, v14, s0
	v_mul_f32_e32 v14, 0xbfb8aa3b, v61
	v_exp_f32_e32 v14, v14
	s_nop 0
	v_add_f32_e32 v14, 1.0, v14
	v_rcp_f32_e32 v14, v14
	s_nop 0
	v_mul_f32_e32 v14, v14, v61
	v_mul_f32_e32 v14, v14, v55
	v_cvt_pk_bf16_f32 v57, v14, s0
	v_mul_f32_e32 v14, 0xbfb8aa3b, v62
	v_exp_f32_e32 v14, v14
	s_nop 0
	v_add_f32_e32 v14, 1.0, v14
	v_rcp_f32_e32 v14, v14
	s_nop 0
	v_mul_f32_e32 v14, v14, v62
	v_mul_f32_e32 v14, v14, v52
	v_cvt_pk_bf16_f32 v54, v14, s0
	v_mul_f32_e32 v14, 0xbfb8aa3b, v63
	v_exp_f32_e32 v14, v14
	s_nop 0
	v_add_f32_e32 v14, 1.0, v14
	v_rcp_f32_e32 v14, v14
	s_nop 0
	v_mul_f32_e32 v14, v14, v63
	v_mul_f32_e32 v14, v14, v53
	v_cvt_pk_bf16_f32 v55, v14, s0
	v_mul_f32_e32 v14, 0xbfb8aa3b, v64
	v_exp_f32_e32 v14, v14
	s_nop 0
	v_add_f32_e32 v14, 1.0, v14
	v_rcp_f32_e32 v14, v14
	s_nop 0
	v_mul_f32_e32 v14, v14, v64
	v_mul_f32_e32 v13, v14, v13
	v_cvt_pk_bf16_f32 v14, v13, s0
	v_mul_f32_e32 v13, 0xbfb8aa3b, v65
	v_exp_f32_e32 v13, v13
	s_nop 0
	v_add_f32_e32 v13, 1.0, v13
	v_rcp_f32_e32 v13, v13
	s_nop 0
	v_mul_f32_e32 v13, v13, v65
	v_mul_f32_e32 v13, v13, v15
	v_cvt_pk_bf16_f32 v15, v13, s0
	s_cbranch_scc1 .LBB0_1554
	v_add_u32_e32 v60, s6, v83
	v_cmp_gt_i32_e64 s[52:53], s15, v60
	v_add_u32_e32 v52, s6, v69
	s_waitcnt vmcnt(8)
	ds_write_b128 v106, v[36:39]
	ds_write_b128 v107, v[40:43]
	ds_write_b128 v109, v[44:47]
	ds_write_b128 v110, v[48:51]
	s_waitcnt lgkmcnt(0)
	s_barrier
	s_cmpk_gt_i32 s6, 0x7d0
	s_cbranch_scc1 .Lrg_fslow2
	s_mov_b64 s[4:5], 0x1000
	v_ashrrev_i32_e32 v53, 31, v52
	v_lshlrev_b64 v[62:63], 11, v[52:53]
	v_lshl_add_u64 v[62:63], v[74:75], 0, v[62:63]
	global_store_short v[62:63], v58, off
	global_store_short v[62:63], v59, off offset:2048
	v_lshl_add_u64 v[62:63], v[62:63], 0, s[4:5]
	global_store_short v[62:63], v56, off
	global_store_short v[62:63], v57, off offset:2048
	v_lshl_add_u64 v[62:63], v[62:63], 0, s[4:5]
	global_store_short v[62:63], v54, off
	global_store_short v[62:63], v55, off offset:2048
	v_lshl_add_u64 v[62:63], v[62:63], 0, s[4:5]
	global_store_short v[62:63], v14, off
	global_store_short v[62:63], v15, off offset:2048
	s_branch .Lrg_fjoin2
.Lrg_fslow2:
	s_and_saveexec_b64 s[4:5], s[52:53]
	s_cbranch_execz .LBB0_1465
	v_ashrrev_i32_e32 v53, 31, v52
	v_lshlrev_b64 v[62:63], 11, v[52:53]
	v_lshl_add_u64 v[62:63], v[74:75], 0, v[62:63]
	global_store_short v[62:63], v58, off

; __device__ __forceinline__ void rglru_unit(const Params& p, const WS& ws, int j, int u, bool dry = false) {
;     ...
; #pragma unroll 1
;   for (int tile = 0; tile < 33; tile += 2) {
;     body(tile, xinA, gavA);
;     if (tile + 1 < 33) body(tile + 1, xinB, gavB);
;   }
.Lrg_fjoin2:
	s_cmp_eq_u32 s101, 1
	s_cbranch_scc0 .Lrg_g2_skip
	s_waitcnt vmcnt(8)
	v_mov_b32_e32 v94, v151
	v_mov_b32_e32 v92, v152
	v_mov_b32_e32 v90, v149
	v_mov_b32_e32 v91, v150
	v_mov_b32_e32 v87, v147
	v_mov_b32_e32 v86, v243
	v_mov_b32_e32 v85, v146
	v_mov_b32_e32 v88, v148
	s_mov_b32 s101, 0
